# mLSTM walk: per-step row/chunk index and all load/store base addresses computed on the scalar unit (wave-uniform), lane offsets precomputed once per job
# baseline (speedup 1.0000x reference)
.LBB0_511:
	v_or_b32_e32 v98, v46, v83
	s_movk_i32 s10, 0xffd4
	v_lshlrev_b32_e32 v46, 4, v98
	v_mov_b32_e32 v47, v1
	v_mul_lo_u32 v194, v186, s10
	s_movk_i32 s10, 0x580
	v_mul_u32_u24_e32 v192, 0x84, v53
	s_mov_b32 s18, 44
	v_add_u32_e32 v193, 44, v52
	v_mov_b32_e32 v99, v1
	v_lshl_add_u64 v[100:101], v[48:49], 1, v[50:51]
	v_lshl_add_u64 v[102:103], s[90:91], 0, v[46:47]
	v_mul_lo_u32 v195, v186, s10
	v_mov_b32_e32 v57, 0
	s_waitcnt vmcnt(0)
	v_mov_b32_e32 v91, v96
	v_mov_b64_e32 v[108:109], v[104:105]
	v_mov_b64_e32 v[110:111], v[106:107]
	v_readfirstlane_b32 s1, v192
	v_lshl_add_u32 v58, v88, 1, v90
	v_add3_u32 v58, v58, v92, v94
	v_add_u32_e32 v58, 0x1000, v58
	v_subrev_u32_e32 v59, s68, v102
	v_lshl_add_u32 v59, v187, 7, v59
	s_sub_u32 s19, s86, s68
	v_lshl_or_b32 v60, v188, 3, v189
	v_lshl_add_u32 v60, v60, 2, s19
	v_lshl_add_u32 v61, v190, 3, v98
	s_sub_u32 s19, s88, s68
	v_lshl_add_u32 v62, v61, 2, s19
	s_sub_u32 s19, s90, s68
	v_lshl_add_u32 v61, v61, 4, s19
	v_lshl_or_b32 v63, v188, 2, v83
	v_mul_u32_u24_e32 v63, 0x180, v63
	v_subrev_u32_e32 v66, s68, v76
	v_add_u32_e32 v63, v63, v66
	v_mul_lo_u32 v66, v191, s16
	v_subrev_u32_e32 v67, s70, v100
	v_add_u32_e32 v66, v66, v67
	v_readfirstlane_b32 s35, v52
	s_nop 0
	s_cmp_lt_i32 s35, 4
	s_cselect_b32 s19, 3, 0x87
	s_sub_i32 s19, s19, s35
	s_cmp_lg_u64 s[62:63], 0
	s_cselect_b32 s19, s35, s19
	s_add_i32 s35, s19, s1
	s_mul_hi_i32 s19, s35, s7
	s_lshr_b32 s14, s19, 31
	s_ashr_i32 s19, s19, 5
	s_add_i32 s19, s19, s14
	s_mul_i32 s14, s19, s17
	s_sub_i32 s14, s35, s14
	s_lshl_b32 s15, s14, 6
	s_lshl_b32 vcc_lo, s19, 13
	s_add_i32 vcc_lo, vcc_lo, s15
	s_addk_i32 vcc_lo, 0xff00
	s_lshl_b32 vcc_hi, s19, 8
	s_add_i32 vcc_hi, vcc_hi, s15
	s_add_i32 vcc_hi, vcc_hi, 0x8000
	s_cmp_gt_i32 s14, 3
	s_cselect_b32 s19, vcc_lo, vcc_hi
	s_mul_i32 s14, s19, s16
	s_add_u32 s84, s70, s14
	s_addc_u32 s85, s71, 0
	v_readfirstlane_b32 s10, v65
	s_cmp_eq_u32 s10, 1
	s_cbranch_scc0 .Lwoff_ml_a
	s_barrier
.Lwoff_ml_a:
.LBB0_512:
.Lml_pre_done:
	s_mov_b64 s[100:101], s[84:85]
	s_waitcnt lgkmcnt(0)
	s_barrier
	s_and_b64 vcc, exec, s[60:61]
	s_cbranch_vccnz .Lml_wait_all
	s_waitcnt vmcnt(2)
	s_branch .Lml_wait_done

.LBB0_524:
	s_or_b64 exec, exec, s[10:11]
	v_add_u32_e32 v196, 1, v52
	v_cmp_lt_i32_e32 vcc, v196, v193
	v_mov_b32_e32 v91, v96
	v_mov_b64_e32 v[108:109], v[104:105]
	v_mov_b64_e32 v[110:111], v[106:107]
	s_and_saveexec_b64 s[10:11], vcc
	s_cbranch_execz .LBB0_541
	v_readfirstlane_b32 s35, v196
	s_nop 0
	s_cmp_lt_i32 s35, 4
	s_cselect_b32 s19, 3, 0x87
	s_sub_i32 s19, s19, s35
	s_cmp_lg_u64 s[62:63], 0
	s_cselect_b32 s19, s35, s19
	s_add_i32 s35, s19, s1
	s_mul_hi_i32 s19, s35, s7
	s_lshr_b32 s14, s19, 31
	s_ashr_i32 s19, s19, 5
	s_add_i32 s19, s19, s14
	s_mul_i32 s14, s19, s17
	s_sub_i32 s14, s35, s14
	s_lshl_b32 s15, s14, 6
	s_lshl_b32 vcc_lo, s19, 13
	s_add_i32 vcc_lo, vcc_lo, s15
	s_addk_i32 vcc_lo, 0xff00
	s_lshl_b32 vcc_hi, s19, 8
	s_add_i32 vcc_hi, vcc_hi, s15
	s_add_i32 vcc_hi, vcc_hi, 0x8000
	s_cmp_gt_i32 s14, 3
	s_cselect_b32 s19, vcc_lo, vcc_hi
	s_mul_i32 s14, s19, s74
	s_add_u32 s26, s70, s14
	s_addc_u32 s27, s71, 0
	s_lshl_b32 s14, s19, 7
	s_add_u32 s44, s68, s14
	s_addc_u32 s45, s69, 0
	s_lshl_b32 s14, s19, 5
	s_add_u32 s46, s68, s14
	s_addc_u32 s47, s69, 0
	s_lshl_b32 s14, s35, 6
	s_add_u32 s48, s68, s14
	s_addc_u32 s49, s69, 0
	s_mul_i32 s14, s35, 0xc00
	s_add_u32 s66, s68, s14
	s_addc_u32 s67, s69, 0
	s_mul_i32 s14, s19, s16
	s_add_u32 s84, s70, s14
	s_addc_u32 s85, s71, 0
	s_and_b64 vcc, exec, s[60:61]
	s_cbranch_vccnz .Lml_ld_a
	global_load_dwordx4 v[14:17], v0, s[26:27] offset:2880
.Lml_ld_a:
	global_load_dwordx4 v[26:29], v0, s[26:27] offset:3648
	s_cbranch_vccnz .Lml_ld_b
	global_load_dwordx4 v[18:21], v84, s[26:27] offset:2880
.Lml_ld_b:
	global_load_dwordx4 v[30:33], v84, s[26:27] offset:3648
	s_cbranch_vccnz .Lml_ld_c
	global_load_dwordx4 v[22:25], v86, s[26:27] offset:2880
.Lml_ld_c:
	global_load_dwordx4 v[38:41], v86, s[26:27] offset:3648
	global_load_dwordx4 v[42:45], v58, s[26:27] offset:320
	global_load_dword v85, v59, s[44:45] offset:12
	global_load_dword v87, v60, s[48:49] offset:4
	s_and_saveexec_b64 s[14:15], s[52:53]
	s_cbranch_execz .LBB0_537
	global_load_dwordx4 v[34:37], v61, s[44:45]
	s_nop 0
	global_load_dword v35, v62, s[46:47]
	global_load_dword v37, v60, s[48:49]
.LBB0_537:
	s_or_b64 exec, exec, s[14:15]
	v_mov_b32_e32 v91, v96
	s_and_saveexec_b64 s[14:15], s[50:51]
	s_cbranch_execz .LBB0_539
	global_load_dword v91, v63, s[66:67]
.LBB0_539:
	s_or_b64 exec, exec, s[14:15]
	s_and_b64 vcc, exec, s[60:61]
	v_mov_b64_e32 v[108:109], v[104:105]
	v_mov_b64_e32 v[110:111], v[106:107]
	s_cbranch_vccnz .LBB0_541
	global_load_dwordx2 v[110:111], v66, s[84:85]
	global_load_dwordx2 v[108:109], v66, s[84:85] offset:32

.LBB0_552:
	s_waitcnt lgkmcnt(0)
	s_barrier
	ds_read2st64_b32 v[202:203], v185 offset0:176 offset1:177
	ds_read2st64_b32 v[204:205], v185 offset0:178 offset1:179
	ds_read_b32 v234, v185 offset:46080
	v_lshlrev_b32_e32 v198, 16, v106
	v_and_b32_e32 v199, 0xffff0000, v106
	v_lshlrev_b32_e32 v106, 16, v107
	s_waitcnt lgkmcnt(2)
	v_mov_b32_e32 v235, v203
	v_mov_b32_e32 v236, v202
	s_waitcnt lgkmcnt(1)
	v_mov_b32_e32 v237, v205
	s_waitcnt lgkmcnt(0)
	v_pk_mul_f32 v[234:235], v[234:235], v[236:237]
	v_max_f32_e32 v95, v204, v204
	v_add_f32_e32 v93, v234, v235
	v_max_f32_e64 v93, |v93|, v95
	v_rcp_f32_e32 v204, v93
	v_and_b32_e32 v107, 0xffff0000, v107
	v_mov_b32_e32 v236, v203
	v_pk_mul_f32 v[198:199], v[236:237], v[198:199] op_sel_hi:[0,1]
	v_pk_mul_f32 v[106:107], v[236:237], v[106:107] op_sel_hi:[0,1]
	v_pk_fma_f32 v[46:47], v[46:47], v[202:203], v[198:199] op_sel_hi:[1,0,1]
	v_pk_fma_f32 v[48:49], v[48:49], v[202:203], v[106:107] op_sel_hi:[1,0,1]
	v_pk_mul_f32 v[46:47], v[46:47], v[204:205] op_sel_hi:[1,0]
	v_pk_mul_f32 v[48:49], v[48:49], v[204:205] op_sel_hi:[1,0]
	v_lshlrev_b32_e32 v200, 16, v104
	v_and_b32_e32 v201, 0xffff0000, v104
	v_lshlrev_b32_e32 v104, 16, v105
	v_and_b32_e32 v105, 0xffff0000, v105
	v_cvt_pk_bf16_f32 v46, v46, v47
	v_cvt_pk_bf16_f32 v47, v48, v49
	global_store_dwordx2 v66, v[46:47], s[100:101]
	v_pk_mul_f32 v[46:47], v[236:237], v[200:201] op_sel_hi:[0,1]
	v_pk_mul_f32 v[48:49], v[236:237], v[104:105] op_sel_hi:[0,1]
	v_pk_fma_f32 v[46:47], v[50:51], v[202:203], v[46:47] op_sel_hi:[1,0,1]
	v_pk_fma_f32 v[48:49], v[52:53], v[202:203], v[48:49] op_sel_hi:[1,0,1]
	v_pk_mul_f32 v[46:47], v[46:47], v[204:205] op_sel_hi:[1,0]
	v_pk_mul_f32 v[48:49], v[48:49], v[204:205] op_sel_hi:[1,0]
	v_cvt_pk_bf16_f32 v46, v46, v47
	v_cvt_pk_bf16_f32 v47, v48, v49
	global_store_dwordx2 v66, v[46:47], s[100:101] offset:32
	s_and_saveexec_b64 s[10:11], s[50:51]
	s_cbranch_execz .LBB0_549
